# band attention unit prologue and epilogue: masked-tile MFMA skip extended to QK(0), QK(NT-1), PV(NT-2), PV(NT-1)
# speedup vs baseline: 1.0068x; 1.0020x over previous
; #define LAS __attribute__((address_space(3)))
; #define SBAR() __builtin_amdgcn_sched_barrier(0)
; template <bool BAND> DI void partialSM(f32x16& p0, f32x16& p1, float& m_reg, float& mn, float& alpha, bool masked, const LAS float* tb, float C) {
;   if (masked) {
; #pragma unroll
;     for (int r = 0; r < 16; ++r) { p0[r] = -1e30f; p1[r] = -1e30f; }
;   } else if (BAND) {
; #pragma unroll
;     for (int r = 0; r < 16; ++r) { const int ko = (r & 3) + 8 * (r >> 2); p0[r] = fmaf(p0[r], C, tb[ko]); }
;     SBAR();
; #pragma unroll
;     for (int r = 0; r < 16; ++r) { const int ko = (r & 3) + 8 * (r >> 2); p1[r] = fmaf(p1[r], C, tb[ko + 32]); }
; template <int NQ> DI void qkt(f32x16& p0, f32x16& p1, const LAS char* Ks, const LAS char* KRs, const bf16x8* qr, int r32, int hi) {
;   p0 = f32x16{}; p1 = f32x16{};
; #pragma unroll
;   for (int d0 = 0; d0 < 8; ++d0) { const int cb = (d0 * 16 + hi * 8) * 2;
;     const bf16x8 b0 = *(const LAS bf16x8*)(Ks + KSWZ(r32, cb));
;     const bf16x8 b1 = *(const LAS bf16x8*)(Ks + KSWZ(32 + r32, cb));
;     p0 = __builtin_amdgcn_mfma_f32_32x32x16_bf16(b0, qr[d0], p0, 0, 0, 0);
;     p1 = __builtin_amdgcn_mfma_f32_32x32x16_bf16(b1, qr[d0], p1, 0, 0, 0); }
.LBB0_278:
	v_lshlrev_b32_e32 v80, 2, v217
	v_or_b32_e32 v1, s44, v80
	v_sub_u32_e32 v56, v1, v2
	v_mul_u32_u24_e32 v1, 0x110, v216
	v_add3_u32 v222, 0, v1, v0
	s_waitcnt lgkmcnt(0)
	s_barrier
	s_ashr_i32 vcc_lo, s42, 7
	s_add_i32 vcc_hi, vcc_lo, s41
	s_cmp_gt_i32 vcc_hi, 0
	s_cbranch_scc1 .Lqsbp_skip
	s_add_i32 vcc_hi, vcc_lo, s40
	s_cmp_lt_i32 vcc_hi, 0
	s_cbranch_scc1 .Lqsbp_skip
	ds_read_b128 v[0:3], v222 offset:41472
	ds_read_b128 v[4:7], v222 offset:32768
	ds_read_b128 v[48:51], v222 offset:32800
	ds_read_b128 v[52:55], v222 offset:41504
	s_waitcnt lgkmcnt(2)
	v_mfma_f32_32x32x16_bf16 v[16:31], v[4:7], v[144:147], 0
	s_ashr_i32 s25, s42, 7
	s_add_i32 s34, s25, s41
	s_cmp_gt_i32 s34, 0
	s_cselect_b64 s[18:19], -1, 0
	s_add_i32 s25, s25, s40
	s_cmp_lt_i32 s25, 0
	s_cselect_b64 s[22:23], -1, 0
	v_mfma_f32_32x32x16_bf16 v[0:15], v[0:3], v[144:147], 0
	s_or_b64 s[18:19], s[18:19], s[22:23]
	v_readlane_b32 s20, v254, 62
	s_and_b64 vcc, exec, s[18:19]
	v_mov_b32_e32 v74, 0xf149f2ca
	v_lshl_add_u32 v221, v56, 2, s20
	v_mov_b32_e32 v75, 0xf149f2ca
	v_mov_b32_e32 v72, 0xf149f2ca
	s_waitcnt lgkmcnt(1)
	v_mfma_f32_32x32x16_bf16 v[16:31], v[48:51], v[140:143], v[16:31]
	v_mov_b32_e32 v73, 0xf149f2ca
	v_mov_b32_e32 v70, 0xf149f2ca
	v_mov_b32_e32 v71, 0xf149f2ca
	v_mov_b32_e32 v68, 0xf149f2ca
	v_mov_b32_e32 v69, 0xf149f2ca
	v_mov_b32_e32 v76, 0xf149f2ca
	v_mov_b32_e32 v77, 0xf149f2ca
	s_waitcnt lgkmcnt(0)
	v_mfma_f32_32x32x16_bf16 v[0:15], v[52:55], v[140:143], v[0:15]
	ds_read_b128 v[48:51], v222 offset:32832
	ds_read_b128 v[52:55], v222 offset:41536
	v_mov_b32_e32 v78, 0xf149f2ca
	v_mov_b32_e32 v79, 0xf149f2ca
	v_mov_b32_e32 v64, 0xf149f2ca
	v_mov_b32_e32 v65, 0xf149f2ca
	v_mov_b32_e32 v66, 0xf149f2ca
	v_mov_b32_e32 v67, 0xf149f2ca
	s_waitcnt lgkmcnt(1)
	v_mfma_f32_32x32x16_bf16 v[16:31], v[48:51], v[136:139], v[16:31]
	v_mov_b32_e32 v62, 0xf149f2ca
	v_mov_b32_e32 v63, 0xf149f2ca
	v_mov_b32_e32 v60, 0xf149f2ca
	v_mov_b32_e32 v61, 0xf149f2ca
	v_mov_b32_e32 v56, 0xf149f2ca
	v_mov_b32_e32 v57, 0xf149f2ca
	v_mov_b32_e32 v58, 0xf149f2ca
	s_waitcnt lgkmcnt(0)
	v_mfma_f32_32x32x16_bf16 v[0:15], v[52:55], v[136:139], v[0:15]
	ds_read_b128 v[48:51], v222 offset:32864
	ds_read_b128 v[52:55], v222 offset:41568
	v_mov_b32_e32 v59, 0xf149f2ca
	s_waitcnt lgkmcnt(1)
	v_mfma_f32_32x32x16_bf16 v[16:31], v[48:51], v[132:135], v[16:31]
	s_waitcnt lgkmcnt(0)
	v_mfma_f32_32x32x16_bf16 v[0:15], v[52:55], v[132:135], v[0:15]
	ds_read_b128 v[48:51], v222 offset:32896
	ds_read_b128 v[52:55], v222 offset:41600
	s_waitcnt lgkmcnt(1)
	v_mfma_f32_32x32x16_bf16 v[16:31], v[48:51], v[128:131], v[16:31]
	s_waitcnt lgkmcnt(0)
	v_mfma_f32_32x32x16_bf16 v[0:15], v[52:55], v[128:131], v[0:15]
	ds_read_b128 v[48:51], v222 offset:32928
	ds_read_b128 v[52:55], v222 offset:41632
	s_waitcnt lgkmcnt(1)
	v_mfma_f32_32x32x16_bf16 v[16:31], v[48:51], v[124:127], v[16:31]
	s_waitcnt lgkmcnt(0)
	v_mfma_f32_32x32x16_bf16 v[0:15], v[52:55], v[124:127], v[0:15]
	ds_read_b128 v[48:51], v222 offset:32960
	ds_read_b128 v[52:55], v222 offset:41664
	s_waitcnt lgkmcnt(1)
	v_mfma_f32_32x32x16_bf16 v[16:31], v[48:51], v[120:123], v[16:31]
	s_waitcnt lgkmcnt(0)
	v_mfma_f32_32x32x16_bf16 v[0:15], v[52:55], v[120:123], v[0:15]
	ds_read_b128 v[48:51], v222 offset:32992
	ds_read_b128 v[52:55], v222 offset:41696
	s_waitcnt lgkmcnt(1)
	v_mfma_f32_32x32x16_bf16 v[16:31], v[48:51], v[116:119], v[16:31]
	v_mov_b32_e32 v48, 0xf149f2ca
	v_mov_b32_e32 v49, 0xf149f2ca
	v_mov_b32_e32 v50, 0xf149f2ca
	v_mov_b32_e32 v51, 0xf149f2ca
	s_waitcnt lgkmcnt(0)
	v_mfma_f32_32x32x16_bf16 v[0:15], v[52:55], v[116:119], v[0:15]
	v_mov_b32_e32 v54, 0xf149f2ca
	v_mov_b32_e32 v55, 0xf149f2ca
	v_mov_b32_e32 v52, 0xf149f2ca
	v_mov_b32_e32 v53, 0xf149f2ca
.Lqsbp_join:
	s_cbranch_vccnz .LBB0_280
	v_add_u32_e32 v48, 0x93c, v221
	v_add_u32_e32 v50, 0x944, v221
	v_add_u32_e32 v52, 0x95c, v221
	v_add_u32_e32 v53, 0x964, v221
	v_add_u32_e32 v56, 0x8fc, v221
	v_add_u32_e32 v57, 0x904, v221
	v_add_u32_e32 v58, 0x91c, v221
	v_add_u32_e32 v59, 0x924, v221
	ds_read2_b32 v[48:49], v48 offset1:1
	ds_read2_b32 v[50:51], v50 offset1:1
	ds_read2_b32 v[54:55], v52 offset1:1
	ds_read2_b32 v[52:53], v53 offset1:1
	ds_read2_b32 v[64:65], v56 offset1:1
	ds_read2_b32 v[66:67], v57 offset1:1
	ds_read2_b32 v[62:63], v58 offset1:1
	ds_read2_b32 v[60:61], v59 offset1:1
	s_waitcnt lgkmcnt(4)
	v_pk_fma_f32 v[52:53], v[30:31], s[36:37], v[52:53] op_sel_hi:[1,0,1]
	v_pk_fma_f32 v[54:55], v[28:29], s[36:37], v[54:55] op_sel_hi:[1,0,1]
	v_pk_fma_f32 v[58:59], v[26:27], s[36:37], v[50:51] op_sel_hi:[1,0,1]
	v_pk_fma_f32 v[56:57], v[24:25], s[36:37], v[48:49] op_sel_hi:[1,0,1]
	s_waitcnt lgkmcnt(0)
	v_pk_fma_f32 v[60:61], v[22:23], s[36:37], v[60:61] op_sel_hi:[1,0,1]
	v_pk_fma_f32 v[62:63], v[20:21], s[36:37], v[62:63] op_sel_hi:[1,0,1]
	v_pk_fma_f32 v[66:67], v[18:19], s[36:37], v[66:67] op_sel_hi:[1,0,1]
	v_pk_fma_f32 v[64:65], v[16:17], s[36:37], v[64:65] op_sel_hi:[1,0,1]
	v_add_u32_e32 v24, 0x97c, v221
	v_add_u32_e32 v26, 0x984, v221
	v_add_u32_e32 v28, 0x99c, v221
	v_add_u32_e32 v30, 0x9a4, v221
	v_add_u32_e32 v16, 0x9bc, v221
	v_add_u32_e32 v18, 0x9c4, v221
	v_add_u32_e32 v20, 0x9dc, v221
	v_add_u32_e32 v22, 0x9e4, v221
	ds_read2_b32 v[16:17], v16 offset1:1
	ds_read2_b32 v[18:19], v18 offset1:1
	ds_read2_b32 v[20:21], v20 offset1:1
	ds_read2_b32 v[22:23], v22 offset1:1
	ds_read2_b32 v[24:25], v24 offset1:1
	ds_read2_b32 v[26:27], v26 offset1:1
	ds_read2_b32 v[28:29], v28 offset1:1
	ds_read2_b32 v[30:31], v30 offset1:1
	s_waitcnt lgkmcnt(4)
	v_pk_fma_f32 v[78:79], v[14:15], s[36:37], v[22:23] op_sel_hi:[1,0,1]
	v_pk_fma_f32 v[76:77], v[12:13], s[36:37], v[20:21] op_sel_hi:[1,0,1]
	v_pk_fma_f32 v[68:69], v[10:11], s[36:37], v[18:19] op_sel_hi:[1,0,1]
	v_pk_fma_f32 v[70:71], v[8:9], s[36:37], v[16:17] op_sel_hi:[1,0,1]
	s_waitcnt lgkmcnt(0)
	v_pk_fma_f32 v[72:73], v[6:7], s[36:37], v[30:31] op_sel_hi:[1,0,1]
	v_pk_fma_f32 v[74:75], v[4:5], s[36:37], v[28:29] op_sel_hi:[1,0,1]
	v_pk_fma_f32 v[50:51], v[2:3], s[36:37], v[26:27] op_sel_hi:[1,0,1]
	v_pk_fma_f32 v[48:49], v[0:1], s[36:37], v[24:25] op_sel_hi:[1,0,1]

; #define LAS __attribute__((address_space(3)))
; template <bool BAND> DI void partialSM(f32x16& p0, f32x16& p1, float& m_reg, float& mn, float& alpha, bool masked, const LAS float* tb, float C) {
;   if (masked) {
; #pragma unroll
;     for (int r = 0; r < 16; ++r) { p0[r] = -1e30f; p1[r] = -1e30f; }
; DI void finishSM(f32x16& p0, f32x16& p1, float alpha, float& l_reg, bf16x8& pa0, bf16x8& pa1, bf16x8& pa2, bf16x8& pa3) {
; #pragma unroll
;   for (int r = 0; r < 16; ++r) p1[r] = __builtin_amdgcn_exp2f(p1[r]);
;   float ps = 0;
; #pragma unroll
;   for (int r = 0; r < 16; ++r) ps += p0[r];
; #pragma unroll
;   for (int r = 0; r < 16; ++r) ps += p1[r];
;   { auto rr = __builtin_amdgcn_permlane32_swap(__float_as_uint(ps), __float_as_uint(ps), false, false);
;     ps = __uint_as_float(rr[0]) + __uint_as_float(rr[1]); }
;   l_reg = l_reg * alpha + ps;
;     ...
;   PK4(p0, 0, pa0); PK4(p0, 8, pa1); PK4(p1, 0, pa2); PK4(p1, 8, pa3);
.Lqsbp_skip:
	s_waitcnt lgkmcnt(0)
	s_ashr_i32 s25, s42, 7
	s_add_i32 s34, s25, s41
	s_cmp_gt_i32 s34, 0
	s_cselect_b64 s[18:19], -1, 0
	s_add_i32 s25, s25, s40
	s_cmp_lt_i32 s25, 0
	s_cselect_b64 s[22:23], -1, 0
	s_or_b64 s[18:19], s[18:19], s[22:23]
	v_readlane_b32 s20, v254, 62
	s_and_b64 vcc, exec, s[18:19]
	v_mov_b32_e32 v74, 0xf149f2ca
	v_lshl_add_u32 v221, v56, 2, s20
	v_mov_b32_e32 v75, 0xf149f2ca
	v_mov_b32_e32 v72, 0xf149f2ca
	v_mov_b32_e32 v73, 0xf149f2ca
	v_mov_b32_e32 v70, 0xf149f2ca
	v_mov_b32_e32 v71, 0xf149f2ca
	v_mov_b32_e32 v68, 0xf149f2ca
	v_mov_b32_e32 v69, 0xf149f2ca
	v_mov_b32_e32 v76, 0xf149f2ca
	v_mov_b32_e32 v77, 0xf149f2ca
	v_mov_b32_e32 v78, 0xf149f2ca
	v_mov_b32_e32 v79, 0xf149f2ca
	v_mov_b32_e32 v64, 0xf149f2ca
	v_mov_b32_e32 v65, 0xf149f2ca
	v_mov_b32_e32 v66, 0xf149f2ca
	v_mov_b32_e32 v67, 0xf149f2ca
	v_mov_b32_e32 v62, 0xf149f2ca
	v_mov_b32_e32 v63, 0xf149f2ca
	v_mov_b32_e32 v60, 0xf149f2ca
	v_mov_b32_e32 v61, 0xf149f2ca
	v_mov_b32_e32 v56, 0xf149f2ca
	v_mov_b32_e32 v57, 0xf149f2ca
	v_mov_b32_e32 v58, 0xf149f2ca
	v_mov_b32_e32 v59, 0xf149f2ca
	v_mov_b32_e32 v48, 0xf149f2ca
	v_mov_b32_e32 v49, 0xf149f2ca
	v_mov_b32_e32 v50, 0xf149f2ca
	v_mov_b32_e32 v51, 0xf149f2ca
	v_mov_b32_e32 v54, 0xf149f2ca
	v_mov_b32_e32 v55, 0xf149f2ca
	v_mov_b32_e32 v52, 0xf149f2ca
	v_mov_b32_e32 v53, 0xf149f2ca
	s_branch .Lqsbp_join
.Lqsbe_skip:
	s_waitcnt lgkmcnt(0)
	v_exp_f32_e32 v110, v78
	v_exp_f32_e32 v111, v79
	v_exp_f32_e32 v114, v76
	v_exp_f32_e32 v115, v77
	v_exp_f32_e32 v212, v74
	v_exp_f32_e32 v213, v75
	v_exp_f32_e32 v72, v72
	v_exp_f32_e32 v73, v73
	v_exp_f32_e32 v214, v70
	v_exp_f32_e32 v215, v71
	v_exp_f32_e32 v224, v69
	v_exp_f32_e32 v222, v68
	v_exp_f32_e32 v138, v64
	v_add_f32_e32 v64, 0, v177
	v_add_f32_e32 v64, v179, v64
	v_add_f32_e32 v64, v175, v64
	v_add_f32_e32 v64, v178, v64
	v_add_f32_e32 v64, v174, v64
	v_add_f32_e32 v64, v176, v64
	v_add_f32_e32 v64, v172, v64
	v_add_f32_e32 v64, v173, v64
	v_add_f32_e32 v64, v169, v64
	v_add_f32_e32 v64, v171, v64
	v_add_f32_e32 v64, v168, v64
	v_add_f32_e32 v64, v170, v64
	v_add_f32_e32 v64, v165, v64
	v_add_f32_e32 v64, v167, v64
	v_add_f32_e32 v64, v164, v64
	v_add_f32_e32 v64, v166, v64
	v_add_f32_e32 v64, v110, v64
	v_add_f32_e32 v64, v111, v64
	v_add_f32_e32 v64, v114, v64
	v_add_f32_e32 v64, v115, v64
	v_add_f32_e32 v64, v212, v64
	v_add_f32_e32 v64, v213, v64
	v_add_f32_e32 v64, v72, v64
	v_add_f32_e32 v64, v73, v64
	v_exp_f32_e32 v136, v66
	v_add_f32_e32 v64, v214, v64
	v_exp_f32_e32 v137, v67
	v_add_f32_e32 v64, v215, v64
	v_add_f32_e32 v64, v222, v64
	v_exp_f32_e32 v139, v65
	v_add_f32_e32 v64, v224, v64
	v_add_f32_e32 v64, v136, v64
	v_add_f32_e32 v64, v137, v64
	v_add_f32_e32 v64, v138, v64
	v_add_f32_e32 v112, v139, v64
	v_mov_b32_e32 v130, v112
	v_cvt_pk_bf16_f32 v64, v177, v179
	v_cvt_pk_bf16_f32 v65, v175, v178
	v_cvt_pk_bf16_f32 v66, v174, v176
	v_cvt_pk_bf16_f32 v67, v172, v173
	v_cvt_pk_bf16_f32 v68, v169, v171
	v_cvt_pk_bf16_f32 v69, v168, v170
	v_cvt_pk_bf16_f32 v70, v165, v167
	v_cvt_pk_bf16_f32 v71, v164, v166
	v_cvt_pk_bf16_f32 v124, v110, v111
	v_cvt_pk_bf16_f32 v125, v114, v115
	v_cvt_pk_bf16_f32 v126, v212, v213
	v_cvt_pk_bf16_f32 v127, v72, v73
	v_permlane32_swap_b32_e32 v112, v130
	v_permlane32_swap_b32_e32 v64, v66
	v_permlane32_swap_b32_e32 v65, v67
	v_permlane32_swap_b32_e32 v68, v70
	v_permlane32_swap_b32_e32 v69, v71
	v_permlane32_swap_b32_e32 v124, v126
	v_permlane32_swap_b32_e32 v125, v127
	v_cvt_pk_bf16_f32 v132, v214, v215
	v_cvt_pk_bf16_f32 v133, v222, v224
	v_cvt_pk_bf16_f32 v134, v136, v137
	v_cvt_pk_bf16_f32 v135, v138, v139
	s_nop 0
	v_permlane32_swap_b32_e32 v132, v134
	v_permlane32_swap_b32_e32 v133, v135
	s_branch .Lqsbe_join
.Lpvbe_skip:
	s_waitcnt lgkmcnt(0)
	s_nop 0
	s_add_i32 s13, s21, -1
	s_cmp_le_i32 s21, s12
	s_cselect_b64 s[14:15], -1, 0
	s_cmp_gt_i32 s13, s25
	s_cselect_b64 s[16:17], -1, 0
	s_or_b64 s[14:15], s[14:15], s[16:17]
	v_mov_b32_e32 v118, 0xf149f2ca
	s_and_b64 vcc, exec, s[14:15]
	v_mov_b32_e32 v119, 0xf149f2ca
	v_mov_b32_e32 v120, 0xf149f2ca
	v_mov_b32_e32 v121, 0xf149f2ca
	v_mov_b32_e32 v114, 0xf149f2ca
	v_mov_b32_e32 v115, 0xf149f2ca
	v_mov_b32_e32 v110, 0xf149f2ca
	v_mov_b32_e32 v111, 0xf149f2ca
	v_mov_b32_e32 v106, 0xf149f2ca
	v_mov_b32_e32 v107, 0xf149f2ca
	v_mov_b32_e32 v70, 0xf149f2ca
	v_mov_b32_e32 v71, 0xf149f2ca
	v_mov_b32_e32 v66, 0xf149f2ca
	v_mov_b32_e32 v67, 0xf149f2ca
	v_mov_b32_e32 v64, 0xf149f2ca
	v_mov_b32_e32 v65, 0xf149f2ca
	v_mov_b32_e32 v128, 0xf149f2ca
	v_mov_b32_e32 v129, 0xf149f2ca
	v_mov_b32_e32 v126, 0xf149f2ca
	v_mov_b32_e32 v127, 0xf149f2ca
	v_mov_b32_e32 v124, 0xf149f2ca
	v_mov_b32_e32 v125, 0xf149f2ca
	v_mov_b32_e32 v122, 0xf149f2ca
	v_mov_b32_e32 v123, 0xf149f2ca
	v_mov_b32_e32 v116, 0xf149f2ca
	v_mov_b32_e32 v117, 0xf149f2ca
	v_mov_b32_e32 v108, 0xf149f2ca
	v_mov_b32_e32 v109, 0xf149f2ca
	v_mov_b32_e32 v72, 0xf149f2ca
	v_mov_b32_e32 v73, 0xf149f2ca
	v_mov_b32_e32 v68, 0xf149f2ca
	v_mov_b32_e32 v69, 0xf149f2ca
	s_branch .Lpvbe_join
.Lpvbf_skip:
	s_waitcnt lgkmcnt(0)
	s_add_i32 s12, 0, 0x4000
	v_add_u32_e32 v75, s12, v219
	s_nop 0
	v_cmp_gt_u32_e32 vcc, 32, v191
	s_branch .Lpvbf_join

; #define LAS __attribute__((address_space(3)))
; DI void finishSM(f32x16& p0, f32x16& p1, float alpha, float& l_reg, bf16x8& pa0, bf16x8& pa1, bf16x8& pa2, bf16x8& pa3) {
; #pragma unroll
;   for (int r = 0; r < 16; ++r) p1[r] = __builtin_amdgcn_exp2f(p1[r]);
;   float ps = 0;
; #pragma unroll
;   for (int r = 0; r < 16; ++r) ps += p0[r];
; #pragma unroll
;   for (int r = 0; r < 16; ++r) ps += p1[r];
;   { auto rr = __builtin_amdgcn_permlane32_swap(__float_as_uint(ps), __float_as_uint(ps), false, false);
;     ps = __uint_as_float(rr[0]) + __uint_as_float(rr[1]); }
;   l_reg = l_reg * alpha + ps;
;     ...
;   PK4(p0, 0, pa0); PK4(p0, 8, pa1); PK4(p1, 0, pa2); PK4(p1, 8, pa3);
;     ...
; }
; template <int NQ> DI void qkt(f32x16& p0, f32x16& p1, const LAS char* Ks, const LAS char* KRs, const bf16x8* qr, int r32, int hi) {
;   p0 = f32x16{}; p1 = f32x16{};
; #pragma unroll
;   for (int d0 = 0; d0 < 8; ++d0) { const int cb = (d0 * 16 + hi * 8) * 2;
;     const bf16x8 b0 = *(const LAS bf16x8*)(Ks + KSWZ(r32, cb));
;     const bf16x8 b1 = *(const LAS bf16x8*)(Ks + KSWZ(32 + r32, cb));
;     p0 = __builtin_amdgcn_mfma_f32_32x32x16_bf16(b0, qr[d0], p0, 0, 0, 0);
;     p1 = __builtin_amdgcn_mfma_f32_32x32x16_bf16(b1, qr[d0], p1, 0, 0, 0); }
.LBB0_299:
	s_max_i32 s12, s34, 0
	s_cmp_le_i32 s21, s12
	s_cbranch_scc1 .Lqsbe_skip
	s_add_i32 vcc_lo, s21, -1
	s_cmp_gt_i32 vcc_lo, s25
	s_cbranch_scc1 .Lqsbe_skip
	v_exp_f32_e32 v110, v78
	v_exp_f32_e32 v111, v79
	v_exp_f32_e32 v114, v76
	v_exp_f32_e32 v115, v77
	ds_read_b128 v[76:79], v222 offset:50176
	v_exp_f32_e32 v212, v74
	v_exp_f32_e32 v213, v75
	v_exp_f32_e32 v72, v72
	v_exp_f32_e32 v73, v73
	s_waitcnt lgkmcnt(0)
	v_mfma_f32_32x32x16_bf16 v[90:105], v[76:79], v[144:147], 0
	ds_read_b128 v[74:77], v222 offset:50208
	v_exp_f32_e32 v214, v70
	v_exp_f32_e32 v215, v71
	v_exp_f32_e32 v224, v69
	s_waitcnt lgkmcnt(0)
	v_mfma_f32_32x32x16_bf16 v[90:105], v[74:77], v[140:143], v[90:105]
	ds_read_b128 v[74:77], v222 offset:58880
	s_waitcnt lgkmcnt(0)
	v_mfma_f32_32x32x16_bf16 v[74:89], v[74:77], v[144:147], 0
	ds_read_b128 v[106:109], v222 offset:58912
	ds_read_b128 v[144:147], v222 offset:50240
	ds_read_b128 v[148:151], v222 offset:50272
	ds_read_b128 v[152:155], v222 offset:58944
	s_waitcnt lgkmcnt(3)
	v_mfma_f32_32x32x16_bf16 v[74:89], v[106:109], v[140:143], v[74:89]
	ds_read_b128 v[106:109], v222 offset:58976
	ds_read_b128 v[140:143], v222 offset:50304
	ds_read_b128 v[156:159], v222 offset:50336
	ds_read_b128 v[160:163], v222 offset:59008
	ds_read_b128 v[192:195], v222 offset:59040
	ds_read_b128 v[196:199], v222 offset:50368
	s_waitcnt lgkmcnt(8)
	v_mfma_f32_32x32x16_bf16 v[90:105], v[144:147], v[136:139], v[90:105]
	ds_read_b128 v[144:147], v222 offset:50400
	ds_read_b128 v[200:203], v222 offset:59072
	ds_read_b128 v[204:207], v222 offset:59104
	v_exp_f32_e32 v222, v68
	s_waitcnt lgkmcnt(9)
	v_mfma_f32_32x32x16_bf16 v[74:89], v[152:155], v[136:139], v[74:89]
	v_exp_f32_e32 v138, v64
	v_add_f32_e32 v64, 0, v177
	v_add_f32_e32 v64, v179, v64
	v_add_f32_e32 v64, v175, v64
	v_add_f32_e32 v64, v178, v64
	v_add_f32_e32 v64, v174, v64
	v_add_f32_e32 v64, v176, v64
	v_mfma_f32_32x32x16_bf16 v[90:105], v[148:151], v[132:135], v[90:105]
	v_add_f32_e32 v64, v172, v64
	v_add_f32_e32 v64, v173, v64
	v_add_f32_e32 v64, v169, v64
	v_add_f32_e32 v64, v171, v64
	v_add_f32_e32 v64, v168, v64
	v_add_f32_e32 v64, v170, v64
	v_add_f32_e32 v64, v165, v64
	s_waitcnt lgkmcnt(8)
	v_mfma_f32_32x32x16_bf16 v[74:89], v[106:109], v[132:135], v[74:89]
	v_add_f32_e32 v64, v167, v64
	v_add_f32_e32 v64, v164, v64
	v_add_f32_e32 v64, v166, v64
	v_add_f32_e32 v64, v110, v64
	v_add_f32_e32 v64, v111, v64
	v_add_f32_e32 v64, v114, v64
	v_add_f32_e32 v64, v115, v64
	s_waitcnt lgkmcnt(7)
	v_mfma_f32_32x32x16_bf16 v[90:105], v[140:143], v[128:131], v[90:105]
	v_add_f32_e32 v64, v212, v64
	v_add_f32_e32 v64, v213, v64
	v_add_f32_e32 v64, v72, v64
	v_add_f32_e32 v64, v73, v64
	v_exp_f32_e32 v136, v66
	v_add_f32_e32 v64, v214, v64
	v_exp_f32_e32 v137, v67
	s_waitcnt lgkmcnt(5)
	v_mfma_f32_32x32x16_bf16 v[74:89], v[160:163], v[128:131], v[74:89]
	v_add_f32_e32 v64, v215, v64
	v_add_f32_e32 v64, v222, v64
	v_exp_f32_e32 v139, v65
	v_add_f32_e32 v64, v224, v64
	v_add_f32_e32 v64, v136, v64
	v_add_f32_e32 v64, v137, v64
	v_add_f32_e32 v64, v138, v64
	v_mfma_f32_32x32x16_bf16 v[90:105], v[156:159], v[124:127], v[90:105]
	v_add_f32_e32 v112, v139, v64
	v_mov_b32_e32 v130, v112
	v_cvt_pk_bf16_f32 v64, v177, v179
	v_cvt_pk_bf16_f32 v65, v175, v178
	v_cvt_pk_bf16_f32 v66, v174, v176
	v_cvt_pk_bf16_f32 v67, v172, v173
	v_cvt_pk_bf16_f32 v68, v169, v171
	s_waitcnt lgkmcnt(4)
	v_mfma_f32_32x32x16_bf16 v[74:89], v[192:195], v[124:127], v[74:89]
	v_cvt_pk_bf16_f32 v69, v168, v170
	v_cvt_pk_bf16_f32 v70, v165, v167
	v_cvt_pk_bf16_f32 v71, v164, v166
	v_cvt_pk_bf16_f32 v124, v110, v111
	v_cvt_pk_bf16_f32 v125, v114, v115
	v_cvt_pk_bf16_f32 v126, v212, v213
	v_cvt_pk_bf16_f32 v127, v72, v73
	s_waitcnt lgkmcnt(3)
	v_mfma_f32_32x32x16_bf16 v[90:105], v[196:199], v[120:123], v[90:105]
	v_permlane32_swap_b32_e32 v112, v130
	v_permlane32_swap_b32_e32 v64, v66
	v_permlane32_swap_b32_e32 v65, v67
	v_permlane32_swap_b32_e32 v68, v70
	s_waitcnt lgkmcnt(1)
	v_mfma_f32_32x32x16_bf16 v[74:89], v[200:203], v[120:123], v[74:89]
	v_permlane32_swap_b32_e32 v69, v71
	v_permlane32_swap_b32_e32 v124, v126
	v_permlane32_swap_b32_e32 v125, v127
	v_cvt_pk_bf16_f32 v132, v214, v215
	v_mfma_f32_32x32x16_bf16 v[90:105], v[144:147], v[116:119], v[90:105]
	v_cvt_pk_bf16_f32 v133, v222, v224
	v_cvt_pk_bf16_f32 v134, v136, v137
	v_cvt_pk_bf16_f32 v135, v138, v139
	s_nop 0
	v_permlane32_swap_b32_e32 v132, v134
	v_permlane32_swap_b32_e32 v133, v135
	s_waitcnt lgkmcnt(0)
	v_mfma_f32_32x32x16_bf16 v[74:89], v[204:207], v[116:119], v[74:89]
; #define LAS __attribute__((address_space(3)))
; #define SBAR() __builtin_amdgcn_sched_barrier(0)
; template <int OFF> DI s16x4 tr_read(int vb) { s16x4 r; asm volatile("ds_read_b64_tr_b16 %0, %1 offset:%2" : "=&v"(r) : "v"(vb), "i"(OFF) : "memory"); return r; }
; template <bool BAND> DI void partialSM(f32x16& p0, f32x16& p1, float& m_reg, float& mn, float& alpha, bool masked, const LAS float* tb, float C) {
;   if (masked) {
; #pragma unroll
;     for (int r = 0; r < 16; ++r) { p0[r] = -1e30f; p1[r] = -1e30f; }
;   } else if (BAND) {
; #pragma unroll
;     for (int r = 0; r < 16; ++r) { const int ko = (r & 3) + 8 * (r >> 2); p0[r] = fmaf(p0[r], C, tb[ko]); }
;     SBAR();
; #pragma unroll
;     for (int r = 0; r < 16; ++r) { const int ko = (r & 3) + 8 * (r >> 2); p1[r] = fmaf(p1[r], C, tb[ko + 32]); }
; template <int D0> DI void pv_one(f32x16& od, int vb, bf16x8 pa0, bf16x8 pa1, bf16x8 pa2, bf16x8 pa3) {
;   const s16x4 l0 = tr_read<v_rd_off(D0, 0, 0)>(vb), h0 = tr_read<v_rd_off(D0, 0, 1)>(vb), l1 = tr_read<v_rd_off(D0, 1, 0)>(vb), h1 = tr_read<v_rd_off(D0, 1, 1)>(vb);
;   const s16x4 l2 = tr_read<v_rd_off(D0, 2, 0)>(vb), h2 = tr_read<v_rd_off(D0, 2, 1)>(vb), l3 = tr_read<v_rd_off(D0, 3, 0)>(vb), h3 = tr_read<v_rd_off(D0, 3, 1)>(vb);
;   asm volatile("s_waitcnt lgkmcnt(0)" ::: "memory"); SBAR();
;     ...
;   od = __builtin_amdgcn_mfma_f32_32x32x16_bf16(pa0, PK(l0, h0), od, 0, 0, 0);
;   od = __builtin_amdgcn_mfma_f32_32x32x16_bf16(pa1, PK(l1, h1), od, 0, 0, 0);
;   od = __builtin_amdgcn_mfma_f32_32x32x16_bf16(pa2, PK(l2, h2), od, 0, 0, 0);
;   od = __builtin_amdgcn_mfma_f32_32x32x16_bf16(pa3, PK(l3, h3), od, 0, 0, 0);
;     ...
; }
; DI void pv_d0(f32x16* o, int vb, bf16x8 pa0, bf16x8 pa1, bf16x8 pa2, bf16x8 pa3) {
;   pv_one<0>(o[0], vb, pa0, pa1, pa2, pa3); pv_one<1>(o[1], vb, pa0, pa1, pa2, pa3); pv_one<2>(o[2], vb, pa0, pa1, pa2, pa3); pv_one<3>(o[3], vb, pa0, pa1, pa2, pa3);
.Lqsbe_join:
	s_add_i32 vcc_lo, s21, -2
	s_cmp_lt_i32 vcc_lo, s12
	s_cbranch_scc1 .Lpvbe_skip
	s_cmp_gt_i32 vcc_lo, s25
	s_cbranch_scc1 .Lpvbe_skip
	ds_read_b64_tr_b16 v[106:107], v223 offset:0
	ds_read_b64_tr_b16 v[108:109], v223 offset:0x800
	ds_read_b64_tr_b16 v[114:115], v223 offset:0x1000
	ds_read_b64_tr_b16 v[116:117], v223 offset:0x1800
	ds_read_b64_tr_b16 v[118:119], v223 offset:0x2000
	ds_read_b64_tr_b16 v[120:121], v223 offset:0x2800
	ds_read_b64_tr_b16 v[136:137], v223 offset:0x3000
	ds_read_b64_tr_b16 v[138:139], v223 offset:0x3800
	s_waitcnt lgkmcnt(0)
	s_nop 0
	v_mfma_f32_32x32x16_bf16 v[48:63], v[64:67], v[106:109], v[48:63]
	ds_read_b64_tr_b16 v[106:107], v223 offset:0x200
	ds_read_b64_tr_b16 v[108:109], v223 offset:0xa00
	v_mfma_f32_32x32x16_bf16 v[48:63], v[68:71], v[114:117], v[48:63]
	ds_read_b64_tr_b16 v[114:115], v223 offset:0x1200
	ds_read_b64_tr_b16 v[116:117], v223 offset:0x1a00
	v_mfma_f32_32x32x16_bf16 v[48:63], v[124:127], v[118:121], v[48:63]
	ds_read_b64_tr_b16 v[118:119], v223 offset:0x2200
	ds_read_b64_tr_b16 v[120:121], v223 offset:0x2a00
	v_mfma_f32_32x32x16_bf16 v[48:63], v[132:135], v[136:139], v[48:63]
	ds_read_b64_tr_b16 v[136:137], v223 offset:0x3200
	ds_read_b64_tr_b16 v[138:139], v223 offset:0x3a00
	s_waitcnt lgkmcnt(0)
	v_mfma_f32_32x32x16_bf16 v[32:47], v[64:67], v[106:109], v[32:47]
	ds_read_b64_tr_b16 v[106:107], v223 offset:0x400
	ds_read_b64_tr_b16 v[108:109], v223 offset:0xc00
	v_mfma_f32_32x32x16_bf16 v[32:47], v[68:71], v[114:117], v[32:47]
	ds_read_b64_tr_b16 v[114:115], v223 offset:0x1400
	ds_read_b64_tr_b16 v[116:117], v223 offset:0x1c00
	v_mfma_f32_32x32x16_bf16 v[32:47], v[124:127], v[118:121], v[32:47]
	ds_read_b64_tr_b16 v[118:119], v223 offset:0x2400
	ds_read_b64_tr_b16 v[120:121], v223 offset:0x2c00
	v_mfma_f32_32x32x16_bf16 v[32:47], v[132:135], v[136:139], v[32:47]
	ds_read_b64_tr_b16 v[136:137], v223 offset:0x3400
	ds_read_b64_tr_b16 v[138:139], v223 offset:0x3c00
	s_waitcnt lgkmcnt(0)
	v_mfma_f32_32x32x16_bf16 v[16:31], v[64:67], v[106:109], v[16:31]
	ds_read_b64_tr_b16 v[106:107], v223 offset:0x600
	ds_read_b64_tr_b16 v[108:109], v223 offset:0xe00
	v_mfma_f32_32x32x16_bf16 v[16:31], v[68:71], v[114:117], v[16:31]
	v_mfma_f32_32x32x16_bf16 v[16:31], v[124:127], v[118:121], v[16:31]
	v_mfma_f32_32x32x16_bf16 v[16:31], v[132:135], v[136:139], v[16:31]
	ds_read_b64_tr_b16 v[136:137], v223 offset:0x1600
	ds_read_b64_tr_b16 v[138:139], v223 offset:0x1e00
	ds_read_b64_tr_b16 v[140:141], v223 offset:0x2600
	ds_read_b64_tr_b16 v[142:143], v223 offset:0x2e00
	ds_read_b64_tr_b16 v[144:145], v223 offset:0x3600
	ds_read_b64_tr_b16 v[146:147], v223 offset:0x3e00
	s_waitcnt lgkmcnt(0)
	v_mfma_f32_32x32x16_bf16 v[0:15], v[64:67], v[106:109], v[0:15]
	s_add_i32 s13, s21, -1
	s_cmp_le_i32 s21, s12
	s_cselect_b64 s[14:15], -1, 0
	s_cmp_gt_i32 s13, s25
	s_cselect_b64 s[16:17], -1, 0
	s_or_b64 s[14:15], s[14:15], s[16:17]
	v_mov_b32_e32 v118, 0xf149f2ca
	v_mfma_f32_32x32x16_bf16 v[0:15], v[68:71], v[136:139], v[0:15]
	s_and_b64 vcc, exec, s[14:15]
	v_mov_b32_e32 v119, 0xf149f2ca
	v_mov_b32_e32 v120, 0xf149f2ca
	v_mov_b32_e32 v121, 0xf149f2ca
	v_mov_b32_e32 v114, 0xf149f2ca
	v_mov_b32_e32 v115, 0xf149f2ca
	v_mov_b32_e32 v110, 0xf149f2ca
	v_mfma_f32_32x32x16_bf16 v[0:15], v[124:127], v[140:143], v[0:15]
	v_mov_b32_e32 v111, 0xf149f2ca
	v_mov_b32_e32 v106, 0xf149f2ca
	v_mov_b32_e32 v107, 0xf149f2ca
	v_mov_b32_e32 v70, 0xf149f2ca
	v_mov_b32_e32 v71, 0xf149f2ca
	v_mov_b32_e32 v66, 0xf149f2ca
	v_mov_b32_e32 v67, 0xf149f2ca
	v_mfma_f32_32x32x16_bf16 v[0:15], v[132:135], v[144:147], v[0:15]
	v_mov_b32_e32 v64, 0xf149f2ca
	v_mov_b32_e32 v65, 0xf149f2ca
	v_mov_b32_e32 v128, 0xf149f2ca
	v_mov_b32_e32 v129, 0xf149f2ca
	v_mov_b32_e32 v126, 0xf149f2ca
	v_mov_b32_e32 v127, 0xf149f2ca
	v_mov_b32_e32 v124, 0xf149f2ca
	v_mov_b32_e32 v125, 0xf149f2ca
	v_mov_b32_e32 v122, 0xf149f2ca
	v_mov_b32_e32 v123, 0xf149f2ca
	v_mov_b32_e32 v116, 0xf149f2ca
	v_mov_b32_e32 v117, 0xf149f2ca
	v_mov_b32_e32 v108, 0xf149f2ca
	v_mov_b32_e32 v109, 0xf149f2ca
	v_mov_b32_e32 v72, 0xf149f2ca
	v_mov_b32_e32 v73, 0xf149f2ca
	v_mov_b32_e32 v68, 0xf149f2ca
	v_mov_b32_e32 v69, 0xf149f2ca
.Lpvbe_join:
	s_cbranch_vccnz .LBB0_301
	v_lshl_add_u32 v120, s13, 8, v221
	v_add_u32_e32 v64, 0x93c, v120
	v_add_u32_e32 v66, 0x944, v120
	v_add_u32_e32 v68, 0x95c, v120
	v_add_u32_e32 v69, 0x964, v120
	v_add_u32_e32 v72, 0x8fc, v120
	v_add_u32_e32 v73, 0x904, v120
	v_add_u32_e32 v108, 0x91c, v120
	v_add_u32_e32 v109, 0x924, v120
	ds_read2_b32 v[64:65], v64 offset1:1
	ds_read2_b32 v[66:67], v66 offset1:1
	ds_read2_b32 v[70:71], v68 offset1:1
	ds_read2_b32 v[68:69], v69 offset1:1
	ds_read2_b32 v[106:107], v72 offset1:1
	ds_read2_b32 v[110:111], v73 offset1:1
	ds_read2_b32 v[114:115], v108 offset1:1
	ds_read2_b32 v[118:119], v109 offset1:1
	s_waitcnt lgkmcnt(4)
	v_pk_fma_f32 v[68:69], v[104:105], s[36:37], v[68:69] op_sel_hi:[1,0,1]
	v_pk_fma_f32 v[72:73], v[102:103], s[36:37], v[70:71] op_sel_hi:[1,0,1]
	v_pk_fma_f32 v[108:109], v[100:101], s[36:37], v[66:67] op_sel_hi:[1,0,1]
	v_pk_fma_f32 v[116:117], v[98:99], s[36:37], v[64:65] op_sel_hi:[1,0,1]
	s_waitcnt lgkmcnt(0)
	v_pk_fma_f32 v[122:123], v[96:97], s[36:37], v[118:119] op_sel_hi:[1,0,1]
	v_pk_fma_f32 v[124:125], v[94:95], s[36:37], v[114:115] op_sel_hi:[1,0,1]
	v_pk_fma_f32 v[126:127], v[92:93], s[36:37], v[110:111] op_sel_hi:[1,0,1]
	v_pk_fma_f32 v[128:129], v[90:91], s[36:37], v[106:107] op_sel_hi:[1,0,1]
	v_add_u32_e32 v92, 0x97c, v120
	v_add_u32_e32 v94, 0x984, v120
	v_add_u32_e32 v96, 0x99c, v120
	v_add_u32_e32 v98, 0x9a4, v120
	v_add_u32_e32 v64, 0x9bc, v120
	v_add_u32_e32 v65, 0x9c4, v120
	v_add_u32_e32 v66, 0x9dc, v120
	v_add_u32_e32 v93, 0x9e4, v120
	ds_read2_b32 v[90:91], v64 offset1:1
	ds_read2_b32 v[70:71], v65 offset1:1
	ds_read2_b32 v[66:67], v66 offset1:1
	ds_read2_b32 v[64:65], v93 offset1:1
	ds_read2_b32 v[92:93], v92 offset1:1
	ds_read2_b32 v[94:95], v94 offset1:1
	ds_read2_b32 v[96:97], v96 offset1:1
	ds_read2_b32 v[98:99], v98 offset1:1
	s_waitcnt lgkmcnt(4)
	v_pk_fma_f32 v[64:65], v[88:89], s[36:37], v[64:65] op_sel_hi:[1,0,1]
	v_pk_fma_f32 v[66:67], v[86:87], s[36:37], v[66:67] op_sel_hi:[1,0,1]
	v_pk_fma_f32 v[70:71], v[84:85], s[36:37], v[70:71] op_sel_hi:[1,0,1]
	v_pk_fma_f32 v[106:107], v[82:83], s[36:37], v[90:91] op_sel_hi:[1,0,1]
	s_waitcnt lgkmcnt(0)
	v_pk_fma_f32 v[110:111], v[80:81], s[36:37], v[98:99] op_sel_hi:[1,0,1]
	v_pk_fma_f32 v[114:115], v[78:79], s[36:37], v[96:97] op_sel_hi:[1,0,1]
	v_pk_fma_f32 v[120:121], v[76:77], s[36:37], v[94:95] op_sel_hi:[1,0,1]
	v_pk_fma_f32 v[118:119], v[74:75], s[36:37], v[92:93] op_sel_hi:[1,0,1]

; #define SBAR() __builtin_amdgcn_sched_barrier(0)
; template <int OFF> DI s16x4 tr_read(int vb) { s16x4 r; asm volatile("ds_read_b64_tr_b16 %0, %1 offset:%2" : "=&v"(r) : "v"(vb), "i"(OFF) : "memory"); return r; }
; template <bool BAND> DI void partialSM(f32x16& p0, f32x16& p1, float& m_reg, float& mn, float& alpha, bool masked, const LAS float* tb, float C) {
;     ...
;   const float mnC = -mn * CC;
; #pragma unroll
;   for (int r = 0; r < 16; ++r) p0[r] = fmaf(p0[r], CC, mnC);
; #pragma unroll
;   for (int r = 0; r < 16; ++r) p1[r] = fmaf(p1[r], CC, mnC);
; #pragma unroll
;   for (int r = 0; r < 16; ++r) p0[r] = __builtin_amdgcn_exp2f(p0[r]);
; }
; DI void finishSM(f32x16& p0, f32x16& p1, float alpha, float& l_reg, bf16x8& pa0, bf16x8& pa1, bf16x8& pa2, bf16x8& pa3) {
; #pragma unroll
;   for (int r = 0; r < 16; ++r) p1[r] = __builtin_amdgcn_exp2f(p1[r]);
;   float ps = 0;
; #pragma unroll
;   for (int r = 0; r < 16; ++r) ps += p0[r];
; #pragma unroll
;   for (int r = 0; r < 16; ++r) ps += p1[r];
;   { auto rr = __builtin_amdgcn_permlane32_swap(__float_as_uint(ps), __float_as_uint(ps), false, false);
;     ps = __uint_as_float(rr[0]) + __uint_as_float(rr[1]); }
;   l_reg = l_reg * alpha + ps;
;     ...
;   PK4(p0, 0, pa0); PK4(p0, 8, pa1); PK4(p1, 0, pa2); PK4(p1, 8, pa3);
; template <int D0> DI void pv_one(f32x16& od, int vb, bf16x8 pa0, bf16x8 pa1, bf16x8 pa2, bf16x8 pa3) {
;   const s16x4 l0 = tr_read<v_rd_off(D0, 0, 0)>(vb), h0 = tr_read<v_rd_off(D0, 0, 1)>(vb), l1 = tr_read<v_rd_off(D0, 1, 0)>(vb), h1 = tr_read<v_rd_off(D0, 1, 1)>(vb);
;   const s16x4 l2 = tr_read<v_rd_off(D0, 2, 0)>(vb), h2 = tr_read<v_rd_off(D0, 2, 1)>(vb), l3 = tr_read<v_rd_off(D0, 3, 0)>(vb), h3 = tr_read<v_rd_off(D0, 3, 1)>(vb);
;   asm volatile("s_waitcnt lgkmcnt(0)" ::: "memory"); SBAR();
;     ...
;   od = __builtin_amdgcn_mfma_f32_32x32x16_bf16(pa0, PK(l0, h0), od, 0, 0, 0);
;   od = __builtin_amdgcn_mfma_f32_32x32x16_bf16(pa1, PK(l1, h1), od, 0, 0, 0);
;   od = __builtin_amdgcn_mfma_f32_32x32x16_bf16(pa2, PK(l2, h2), od, 0, 0, 0);
;   od = __builtin_amdgcn_mfma_f32_32x32x16_bf16(pa3, PK(l3, h3), od, 0, 0, 0);
;     ...
; }
; DI void pv_d0(f32x16* o, int vb, bf16x8 pa0, bf16x8 pa1, bf16x8 pa2, bf16x8 pa3) {
;   pv_one<0>(o[0], vb, pa0, pa1, pa2, pa3); pv_one<1>(o[1], vb, pa0, pa1, pa2, pa3); pv_one<2>(o[2], vb, pa0, pa1, pa2, pa3); pv_one<3>(o[3], vb, pa0, pa1, pa2, pa3);
.LBB0_305:
	v_cndmask_b32_e64 v87, v75, v228, s[42:43]
	v_sub_f32_e32 v75, v128, v87
	v_sub_f32_e32 v76, v129, v87
	v_exp_f32_e32 v84, v75
	v_sub_f32_e32 v77, v126, v87
	v_exp_f32_e32 v86, v76
	v_sub_f32_e32 v78, v127, v87
	v_exp_f32_e32 v82, v77
	v_sub_f32_e32 v79, v124, v87
	v_exp_f32_e32 v85, v78
	v_sub_f32_e32 v64, v64, v87
	v_sub_f32_e32 v81, v125, v87
	v_exp_f32_e32 v80, v79
	v_exp_f32_e32 v101, v64
	v_add_f32_e32 v64, 0, v84
	v_sub_f32_e32 v88, v122, v87
	v_exp_f32_e32 v83, v81
	v_add_f32_e32 v64, v86, v64
	v_sub_f32_e32 v89, v123, v87
	v_exp_f32_e32 v79, v88
	v_add_f32_e32 v64, v82, v64
	v_sub_f32_e32 v90, v116, v87
	v_exp_f32_e32 v81, v89
	v_add_f32_e32 v64, v85, v64
	v_sub_f32_e32 v91, v117, v87
	v_exp_f32_e32 v76, v90
	v_add_f32_e32 v64, v80, v64
	v_sub_f32_e32 v92, v108, v87
	v_exp_f32_e32 v78, v91
	v_add_f32_e32 v64, v83, v64
	v_sub_f32_e32 v93, v109, v87
	v_sub_f32_e32 v94, v73, v87
	v_exp_f32_e32 v73, v92
	v_add_f32_e32 v64, v79, v64
	v_sub_f32_e32 v72, v72, v87
	v_exp_f32_e32 v77, v93
	v_add_f32_e32 v64, v81, v64
	v_sub_f32_e32 v95, v69, v87
	v_exp_f32_e32 v69, v72
	v_add_f32_e32 v64, v76, v64
	v_sub_f32_e32 v68, v68, v87
	v_exp_f32_e32 v75, v94
	v_add_f32_e32 v64, v78, v64
	v_exp_f32_e32 v68, v68
	v_add_f32_e32 v64, v73, v64
	v_exp_f32_e32 v72, v95
	v_sub_f32_e32 v88, v118, v87
	v_add_f32_e32 v64, v77, v64
	v_sub_f32_e32 v89, v119, v87
	v_exp_f32_e32 v88, v88
	v_add_f32_e32 v64, v69, v64
	v_sub_f32_e32 v90, v120, v87
	v_exp_f32_e32 v89, v89
	v_add_f32_e32 v64, v75, v64
	v_sub_f32_e32 v91, v121, v87
	v_exp_f32_e32 v90, v90
	v_add_f32_e32 v64, v68, v64
	v_sub_f32_e32 v92, v114, v87
	v_exp_f32_e32 v91, v91
	v_add_f32_e32 v64, v72, v64
	v_sub_f32_e32 v93, v115, v87
	v_exp_f32_e32 v92, v92
	v_add_f32_e32 v64, v88, v64
	v_sub_f32_e32 v94, v110, v87
	v_exp_f32_e32 v93, v93
	v_add_f32_e32 v64, v89, v64
	v_sub_f32_e32 v95, v111, v87
	v_exp_f32_e32 v94, v94
	v_add_f32_e32 v64, v90, v64
	v_sub_f32_e32 v96, v106, v87
	v_exp_f32_e32 v95, v95
	v_add_f32_e32 v64, v91, v64
	v_sub_f32_e32 v97, v107, v87
	v_exp_f32_e32 v96, v96
	v_add_f32_e32 v64, v92, v64
	v_sub_f32_e32 v70, v70, v87
	v_exp_f32_e32 v97, v97
	v_add_f32_e32 v64, v93, v64
	v_sub_f32_e32 v71, v71, v87
	v_exp_f32_e32 v98, v70
	v_add_f32_e32 v64, v94, v64
	v_sub_f32_e32 v66, v66, v87
	v_exp_f32_e32 v71, v71
	v_add_f32_e32 v64, v95, v64
	v_sub_f32_e32 v67, v67, v87
	v_exp_f32_e32 v99, v66
	v_add_f32_e32 v64, v96, v64
	v_exp_f32_e32 v100, v67
	v_add_f32_e32 v64, v97, v64
	v_sub_f32_e32 v65, v65, v87
	v_add_f32_e32 v64, v98, v64
	v_exp_f32_e32 v102, v65
	v_add_f32_e32 v64, v71, v64
	v_add_f32_e32 v64, v99, v64
	v_add_f32_e32 v64, v100, v64
	v_add_f32_e32 v64, v101, v64
	v_add_f32_e32 v64, v102, v64
	v_mov_b32_e32 v65, v64
	s_nop 1
	v_permlane32_swap_b32_e32 v64, v65
	v_cvt_pk_bf16_f32 v84, v84, v86
	v_cvt_pk_bf16_f32 v85, v82, v85
	v_cvt_pk_bf16_f32 v86, v80, v83
	v_cvt_pk_bf16_f32 v87, v79, v81
	v_cvt_pk_bf16_f32 v76, v76, v78
	v_cvt_pk_bf16_f32 v77, v73, v77
	v_cvt_pk_bf16_f32 v78, v69, v75
	v_cvt_pk_bf16_f32 v79, v68, v72
	v_cvt_pk_bf16_f32 v66, v88, v89
	v_cvt_pk_bf16_f32 v67, v90, v91
	v_cvt_pk_bf16_f32 v68, v92, v93
	v_cvt_pk_bf16_f32 v69, v94, v95
	v_cvt_pk_bf16_f32 v70, v96, v97
	v_cvt_pk_bf16_f32 v71, v98, v71
	v_cvt_pk_bf16_f32 v72, v99, v100
	v_cvt_pk_bf16_f32 v73, v101, v102
	s_nop 0
	v_permlane32_swap_b32_e32 v84, v86
	v_permlane32_swap_b32_e32 v85, v87
	v_permlane32_swap_b32_e32 v76, v78
	v_permlane32_swap_b32_e32 v77, v79
	v_permlane32_swap_b32_e32 v66, v68
	v_permlane32_swap_b32_e32 v67, v69
	v_permlane32_swap_b32_e32 v70, v72
	v_permlane32_swap_b32_e32 v71, v73
	s_max_i32 vcc_lo, s34, 0
	s_cmp_le_i32 s21, vcc_lo
	s_cbranch_scc1 .Lpvbf_skip
	s_add_i32 vcc_lo, s21, -1
	s_cmp_gt_i32 vcc_lo, s25
	s_cbranch_scc1 .Lpvbf_skip
	s_add_i32 s12, 0, 0x4000
	v_add_u32_e32 v75, s12, v219
	ds_read_b64_tr_b16 v[80:81], v75 offset:0
	ds_read_b64_tr_b16 v[82:83], v75 offset:0x800
	ds_read_b64_tr_b16 v[88:89], v75 offset:0x1000
	ds_read_b64_tr_b16 v[90:91], v75 offset:0x1800
	ds_read_b64_tr_b16 v[92:93], v75 offset:0x2000
	ds_read_b64_tr_b16 v[94:95], v75 offset:0x2800
	ds_read_b64_tr_b16 v[96:97], v75 offset:0x3000
	ds_read_b64_tr_b16 v[98:99], v75 offset:0x3800
	s_waitcnt lgkmcnt(0)
	s_nop 0
	v_mfma_f32_32x32x16_bf16 v[48:63], v[84:87], v[80:83], v[48:63]
	ds_read_b64_tr_b16 v[80:81], v75 offset:0x200
	ds_read_b64_tr_b16 v[82:83], v75 offset:0xa00
	v_mfma_f32_32x32x16_bf16 v[48:63], v[76:79], v[88:91], v[48:63]
	ds_read_b64_tr_b16 v[88:89], v75 offset:0x1200
	ds_read_b64_tr_b16 v[90:91], v75 offset:0x1a00
	v_mfma_f32_32x32x16_bf16 v[48:63], v[66:69], v[92:95], v[48:63]
	ds_read_b64_tr_b16 v[92:93], v75 offset:0x2200
	ds_read_b64_tr_b16 v[94:95], v75 offset:0x2a00
	v_mfma_f32_32x32x16_bf16 v[48:63], v[70:73], v[96:99], v[48:63]
	ds_read_b64_tr_b16 v[96:97], v75 offset:0x3200
	ds_read_b64_tr_b16 v[98:99], v75 offset:0x3a00
	s_waitcnt lgkmcnt(0)
	v_mfma_f32_32x32x16_bf16 v[32:47], v[84:87], v[80:83], v[32:47]
	ds_read_b64_tr_b16 v[80:81], v75 offset:0x400
	ds_read_b64_tr_b16 v[82:83], v75 offset:0xc00
	v_mfma_f32_32x32x16_bf16 v[32:47], v[76:79], v[88:91], v[32:47]
	ds_read_b64_tr_b16 v[88:89], v75 offset:0x1400
	ds_read_b64_tr_b16 v[90:91], v75 offset:0x1c00
	v_mfma_f32_32x32x16_bf16 v[32:47], v[66:69], v[92:95], v[32:47]
	ds_read_b64_tr_b16 v[92:93], v75 offset:0x2400
	ds_read_b64_tr_b16 v[94:95], v75 offset:0x2c00
	v_mfma_f32_32x32x16_bf16 v[32:47], v[70:73], v[96:99], v[32:47]
	ds_read_b64_tr_b16 v[96:97], v75 offset:0x3400
	ds_read_b64_tr_b16 v[98:99], v75 offset:0x3c00
	s_waitcnt lgkmcnt(0)
	v_mfma_f32_32x32x16_bf16 v[16:31], v[84:87], v[80:83], v[16:31]
	ds_read_b64_tr_b16 v[80:81], v75 offset:0x600
	ds_read_b64_tr_b16 v[82:83], v75 offset:0xe00
	v_mfma_f32_32x32x16_bf16 v[16:31], v[76:79], v[88:91], v[16:31]
	ds_read_b64_tr_b16 v[88:89], v75 offset:0x1600
	ds_read_b64_tr_b16 v[90:91], v75 offset:0x1e00
	v_mfma_f32_32x32x16_bf16 v[16:31], v[66:69], v[92:95], v[16:31]
	ds_read_b64_tr_b16 v[92:93], v75 offset:0x2600
	ds_read_b64_tr_b16 v[94:95], v75 offset:0x2e00
	v_mfma_f32_32x32x16_bf16 v[16:31], v[70:73], v[96:99], v[16:31]
	ds_read_b64_tr_b16 v[96:97], v75 offset:0x3600
	ds_read_b64_tr_b16 v[98:99], v75 offset:0x3e00
	s_waitcnt lgkmcnt(0)
	v_mfma_f32_32x32x16_bf16 v[0:15], v[84:87], v[80:83], v[0:15]
	v_cmp_gt_u32_e32 vcc, 32, v191
	v_mfma_f32_32x32x16_bf16 v[0:15], v[76:79], v[88:91], v[0:15]
	v_mfma_f32_32x32x16_bf16 v[0:15], v[66:69], v[92:95], v[0:15]
	v_mfma_f32_32x32x16_bf16 v[0:15], v[70:73], v[96:99], v[0:15]
.Lpvbf_join:
	s_and_saveexec_b64 s[12:13], vcc
	s_cbranch_execz .LBB0_307
	v_add_f32_e32 v66, v112, v130
	v_fmac_f32_e32 v66, v220, v234
	v_add_f32_e32 v64, v64, v65
	v_lshl_add_u32 v67, v216, 2, s20
	v_fmac_f32_e32 v64, v66, v74
	ds_write_b32 v67, v64
